# attention loop 1 row-sum chains use packed f32 adds (31 adds -> 16 per tile)
# baseline (speedup 1.0000x reference)
.LBB0_1358:
	s_and_b32 s2, s29, 3
	s_mulk_i32 s2, 0x3000
	v_add_u32_e32 v84, s2, v180
	ds_read_b128 v[80:83], v84
	ds_read_b128 v[184:187], v84 offset:512
	ds_read_b128 v[204:207], v84 offset:2048
	ds_read_b128 v[208:211], v84 offset:2560
	ds_read_b128 v[218:221], v84 offset:4096
	ds_read_b128 v[222:225], v84 offset:4608
	ds_read_b128 v[226:229], v84 offset:6144
	ds_read_b128 v[230:233], v84 offset:6656
	s_and_b32 s2, s75, 0x6000
	v_pk_add_f32 v[84:85], v[64:65], v[66:67]
	v_add_u32_e32 v183, s2, v199
	ds_read_b64_tr_b16 v[176:177], v183 offset:49152
	ds_read_b64_tr_b16 v[178:179], v183 offset:49664
	s_waitcnt lgkmcnt(9)
	v_mfma_f32_32x32x16_bf16 v[96:111], v[80:83], v[168:171], v[32:47]
	v_pk_add_f32 v[84:85], v[68:69], v[84:85]
	v_cvt_pk_bf16_f32 v148, v64, v65
	v_cvt_pk_bf16_f32 v149, v66, v67
	ds_read_b64_tr_b16 v[172:173], v183 offset:53248
	ds_read_b64_tr_b16 v[174:175], v183 offset:53760
	v_pk_add_f32 v[64:65], v[70:71], v[84:85]
	s_waitcnt lgkmcnt(10)
	v_mfma_f32_32x32x16_bf16 v[80:95], v[184:187], v[168:171], v[32:47]
	v_pk_add_f32 v[140:141], v[72:73], v[64:65]
	v_cvt_pk_bf16_f32 v150, v68, v69
	v_cvt_pk_bf16_f32 v151, v70, v71
	ds_read_b64_tr_b16 v[64:65], v183 offset:50176
	ds_read_b64_tr_b16 v[66:67], v183 offset:50688
	s_waitcnt lgkmcnt(11)
	v_mfma_f32_32x32x16_bf16 v[96:111], v[204:207], v[164:167], v[96:111]
	v_pk_add_f32 v[68:69], v[74:75], v[140:141]
	v_pk_add_f32 v[140:141], v[76:77], v[68:69]
	v_cvt_pk_bf16_f32 v152, v72, v73
	v_cvt_pk_bf16_f32 v153, v74, v75
	ds_read_b64_tr_b16 v[68:69], v183 offset:54272
	ds_read_b64_tr_b16 v[70:71], v183 offset:54784
	s_waitcnt lgkmcnt(12)
	v_mfma_f32_32x32x16_bf16 v[80:95], v[208:211], v[164:167], v[80:95]
	v_pk_add_f32 v[72:73], v[78:79], v[140:141]
	v_pk_add_f32 v[140:141], v[48:49], v[72:73]
	v_cvt_pk_bf16_f32 v154, v76, v77
	v_cvt_pk_bf16_f32 v155, v78, v79
	ds_read_b64_tr_b16 v[72:73], v183 offset:51200
	ds_read_b64_tr_b16 v[74:75], v183 offset:51712
	s_waitcnt lgkmcnt(13)
	v_mfma_f32_32x32x16_bf16 v[96:111], v[218:221], v[160:163], v[96:111]
	v_pk_add_f32 v[76:77], v[50:51], v[140:141]
	v_pk_add_f32 v[76:77], v[52:53], v[76:77]
	v_cvt_pk_bf16_f32 v144, v48, v49
	v_cvt_pk_bf16_f32 v145, v50, v51
	ds_read_b64_tr_b16 v[48:49], v183 offset:55296
	ds_read_b64_tr_b16 v[50:51], v183 offset:55808
	s_waitcnt lgkmcnt(14)
	v_mfma_f32_32x32x16_bf16 v[80:95], v[222:225], v[160:163], v[80:95]
	v_pk_add_f32 v[76:77], v[54:55], v[76:77]
	v_pk_add_f32 v[76:77], v[56:57], v[76:77]
	v_cvt_pk_bf16_f32 v146, v52, v53
	v_cvt_pk_bf16_f32 v147, v54, v55
	ds_read_b64_tr_b16 v[52:53], v183 offset:52224
	ds_read_b64_tr_b16 v[54:55], v183 offset:52736
	s_waitcnt lgkmcnt(14)
	v_mfma_f32_32x32x16_bf16 v[96:111], v[226:229], v[156:159], v[96:111]
	v_pk_add_f32 v[76:77], v[58:59], v[76:77]
	v_pk_add_f32 v[76:77], v[60:61], v[76:77]
	v_cvt_pk_bf16_f32 v140, v56, v57
	v_cvt_pk_bf16_f32 v141, v58, v59
	ds_read_b64_tr_b16 v[56:57], v183 offset:56320
	ds_read_b64_tr_b16 v[58:59], v183 offset:56832
	v_mfma_f32_32x32x16_bf16 v[80:95], v[230:233], v[156:159], v[80:95]
	v_pk_add_f32 v[76:77], v[62:63], v[76:77]
	v_add_f32_e32 v76, v76, v77
	v_cvt_pk_bf16_f32 v142, v60, v61
	v_cvt_pk_bf16_f32 v143, v62, v63
	s_cmp_gt_u32 s29, 7
	s_cselect_b64 s[2:3], -1, 0
	s_add_i32 s54, s73, s28
	s_and_b64 s[2:3], s[48:49], s[2:3]
	s_add_i32 s50, s54, -13
	s_cmp_lt_u32 s50, -3
	s_cselect_b64 s[50:51], -1, 0
	s_and_b64 s[2:3], s[2:3], s[50:51]
	s_andn2_b64 vcc, exec, s[2:3]
	s_cbranch_vccnz .LBB0_1360
	v_cmp_lt_u32_e32 vcc, s78, v182
	v_add_u32_e32 v60, 32, v182
	s_nop 0
	v_cndmask_b32_e32 v96, v253, v96, vcc
	v_cmp_lt_u32_e32 vcc, s78, v60
	v_add_u32_e32 v60, 1, v182
	s_nop 0
	v_cndmask_b32_e32 v80, v253, v80, vcc
	v_cmp_lt_u32_e32 vcc, s78, v60
	v_add_u32_e32 v60, 33, v182
	s_nop 0
	v_cndmask_b32_e32 v97, v253, v97, vcc
	v_cmp_lt_u32_e32 vcc, s78, v60
	v_add_u32_e32 v60, 2, v182
	s_nop 0
	v_cndmask_b32_e32 v81, v253, v81, vcc
	v_cmp_lt_u32_e32 vcc, s78, v60
	v_add_u32_e32 v60, 34, v182
	s_nop 0
	v_cndmask_b32_e32 v98, v253, v98, vcc
	v_cmp_lt_u32_e32 vcc, s78, v60
	v_add_u32_e32 v60, 3, v182
	s_nop 0
	v_cndmask_b32_e32 v82, v253, v82, vcc
	v_cmp_lt_u32_e32 vcc, s78, v60
	v_add_u32_e32 v60, 35, v182
	s_nop 0
	v_cndmask_b32_e32 v99, v253, v99, vcc
	v_cmp_lt_u32_e32 vcc, s78, v60
	v_add_u32_e32 v60, 8, v182
	s_nop 0
	v_cndmask_b32_e32 v83, v253, v83, vcc
	v_cmp_lt_u32_e32 vcc, s78, v60
	v_add_u32_e32 v60, 40, v182
	s_nop 0
	v_cndmask_b32_e32 v100, v253, v100, vcc
	v_cmp_lt_u32_e32 vcc, s78, v60
	v_add_u32_e32 v60, 9, v182
	s_nop 0
	v_cndmask_b32_e32 v84, v253, v84, vcc
	v_cmp_lt_u32_e32 vcc, s78, v60
	v_add_u32_e32 v60, 41, v182
	s_nop 0
	v_cndmask_b32_e32 v101, v253, v101, vcc
	v_cmp_lt_u32_e32 vcc, s78, v60
	v_add_u32_e32 v60, 10, v182
	s_nop 0
	v_cndmask_b32_e32 v85, v253, v85, vcc
	v_cmp_lt_u32_e32 vcc, s78, v60
	v_add_u32_e32 v60, 42, v182
	s_nop 0
	v_cndmask_b32_e32 v102, v253, v102, vcc
	v_cmp_lt_u32_e32 vcc, s78, v60
	v_add_u32_e32 v60, 11, v182
	s_nop 0
	v_cndmask_b32_e32 v86, v253, v86, vcc
	v_cmp_lt_u32_e32 vcc, s78, v60
	v_add_u32_e32 v60, 43, v182
	s_nop 0
	v_cndmask_b32_e32 v103, v253, v103, vcc
	v_cmp_lt_u32_e32 vcc, s78, v60
	v_add_u32_e32 v60, 16, v182
	s_nop 0
	v_cndmask_b32_e32 v87, v253, v87, vcc
	v_cmp_lt_u32_e32 vcc, s78, v60
	v_add_u32_e32 v60, 48, v182
	s_nop 0
	v_cndmask_b32_e32 v104, v253, v104, vcc
	v_cmp_lt_u32_e32 vcc, s78, v60
	v_add_u32_e32 v60, 17, v182
	s_nop 0
	v_cndmask_b32_e32 v88, v253, v88, vcc
	v_cmp_lt_u32_e32 vcc, s78, v60
	v_add_u32_e32 v60, 49, v182
	s_nop 0
	v_cndmask_b32_e32 v105, v253, v105, vcc
	v_cmp_lt_u32_e32 vcc, s78, v60
	v_add_u32_e32 v60, 18, v182
	s_nop 0
	v_cndmask_b32_e32 v89, v253, v89, vcc
	v_cmp_lt_u32_e32 vcc, s78, v60
	v_add_u32_e32 v60, 50, v182
	s_nop 0
	v_cndmask_b32_e32 v106, v253, v106, vcc
	v_cmp_lt_u32_e32 vcc, s78, v60
	v_add_u32_e32 v60, 19, v182
	s_nop 0
	v_cndmask_b32_e32 v90, v253, v90, vcc
	v_cmp_lt_u32_e32 vcc, s78, v60
	v_add_u32_e32 v60, 51, v182
	s_nop 0
	v_cndmask_b32_e32 v107, v253, v107, vcc
	v_cmp_lt_u32_e32 vcc, s78, v60
	v_add_u32_e32 v60, 24, v182
	s_nop 0
	v_cndmask_b32_e32 v91, v253, v91, vcc
	v_cmp_lt_u32_e32 vcc, s78, v60
	v_add_u32_e32 v60, 56, v182
	s_nop 0
	v_cndmask_b32_e32 v108, v253, v108, vcc
	v_cmp_lt_u32_e32 vcc, s78, v60
	v_add_u32_e32 v60, 25, v182
	s_nop 0
	v_cndmask_b32_e32 v92, v253, v92, vcc
	v_cmp_lt_u32_e32 vcc, s78, v60
	v_add_u32_e32 v60, 57, v182
	s_nop 0
	v_cndmask_b32_e32 v109, v253, v109, vcc
	v_cmp_lt_u32_e32 vcc, s78, v60
	v_add_u32_e32 v60, 26, v182
	s_nop 0
	v_cndmask_b32_e32 v93, v253, v93, vcc
	v_cmp_lt_u32_e32 vcc, s78, v60
	v_add_u32_e32 v60, 58, v182
	s_nop 0
	v_cndmask_b32_e32 v110, v253, v110, vcc
	v_cmp_lt_u32_e32 vcc, s78, v60
	v_add_u32_e32 v60, 27, v182
	s_nop 0
	v_cndmask_b32_e32 v94, v253, v94, vcc
	v_cmp_lt_u32_e32 vcc, s78, v60
	v_add_u32_e32 v60, 59, v182
	s_nop 0
	v_cndmask_b32_e32 v111, v253, v111, vcc
	v_cmp_lt_u32_e32 vcc, s78, v60
	s_nop 1
	v_cndmask_b32_e32 v95, v253, v95, vcc

.LBB0_1374:
	s_add_i32 s2, s28, -2
	s_and_b32 s2, s2, 3
	s_mulk_i32 s2, 0x3000
	v_add_u32_e32 v52, s2, v180
	ds_read_b128 v[48:51], v52
	ds_read_b128 v[184:187], v52 offset:512
	ds_read_b128 v[204:207], v52 offset:2048
	ds_read_b128 v[208:211], v52 offset:2560
	ds_read_b128 v[218:221], v52 offset:4096
	ds_read_b128 v[222:225], v52 offset:4608
	ds_read_b128 v[226:229], v52 offset:6144
	ds_read_b128 v[230:233], v52 offset:6656
	s_add_i32 s2, s75, 0xffffa000
	s_and_b32 s2, s2, 0x6000
	v_pk_add_f32 v[52:53], v[96:97], v[98:99]
	v_add_u32_e32 v203, s2, v199
	ds_read_b64_tr_b16 v[176:177], v203 offset:49152
	ds_read_b64_tr_b16 v[178:179], v203 offset:49664
	s_waitcnt lgkmcnt(9)
	v_mfma_f32_32x32x16_bf16 v[64:79], v[48:51], v[168:171], v[32:47]
	v_pk_add_f32 v[52:53], v[100:101], v[52:53]
	v_cvt_pk_bf16_f32 v148, v96, v97
	v_cvt_pk_bf16_f32 v149, v98, v99
	ds_read_b64_tr_b16 v[172:173], v203 offset:53248
	ds_read_b64_tr_b16 v[174:175], v203 offset:53760
	v_pk_add_f32 v[48:49], v[102:103], v[52:53]
	v_pk_add_f32 v[140:141], v[104:105], v[48:49]
	s_waitcnt lgkmcnt(10)
	v_mfma_f32_32x32x16_bf16 v[48:63], v[184:187], v[168:171], v[32:47]
	v_cvt_pk_bf16_f32 v150, v100, v101
	v_cvt_pk_bf16_f32 v151, v102, v103
	ds_read_b64_tr_b16 v[96:97], v203 offset:50176
	ds_read_b64_tr_b16 v[98:99], v203 offset:50688
	s_waitcnt lgkmcnt(11)
	v_mfma_f32_32x32x16_bf16 v[64:79], v[204:207], v[164:167], v[64:79]
	v_pk_add_f32 v[100:101], v[106:107], v[140:141]
	v_pk_add_f32 v[140:141], v[108:109], v[100:101]
	v_cvt_pk_bf16_f32 v152, v104, v105
	v_cvt_pk_bf16_f32 v153, v106, v107
	ds_read_b64_tr_b16 v[100:101], v203 offset:54272
	ds_read_b64_tr_b16 v[102:103], v203 offset:54784
	s_waitcnt lgkmcnt(12)
	v_mfma_f32_32x32x16_bf16 v[48:63], v[208:211], v[164:167], v[48:63]
	v_pk_add_f32 v[104:105], v[110:111], v[140:141]
	v_pk_add_f32 v[140:141], v[80:81], v[104:105]
	v_cvt_pk_bf16_f32 v154, v108, v109
	v_cvt_pk_bf16_f32 v155, v110, v111
	ds_read_b64_tr_b16 v[104:105], v203 offset:51200
	ds_read_b64_tr_b16 v[106:107], v203 offset:51712
	s_waitcnt lgkmcnt(13)
	v_mfma_f32_32x32x16_bf16 v[64:79], v[218:221], v[160:163], v[64:79]
	v_pk_add_f32 v[108:109], v[82:83], v[140:141]
	v_pk_add_f32 v[108:109], v[84:85], v[108:109]
	v_cvt_pk_bf16_f32 v144, v80, v81
	v_cvt_pk_bf16_f32 v145, v82, v83
	ds_read_b64_tr_b16 v[80:81], v203 offset:55296
	ds_read_b64_tr_b16 v[82:83], v203 offset:55808
	s_waitcnt lgkmcnt(14)
	v_mfma_f32_32x32x16_bf16 v[48:63], v[222:225], v[160:163], v[48:63]
	v_pk_add_f32 v[108:109], v[86:87], v[108:109]
	v_pk_add_f32 v[108:109], v[88:89], v[108:109]
	v_cvt_pk_bf16_f32 v146, v84, v85
	v_cvt_pk_bf16_f32 v147, v86, v87
	ds_read_b64_tr_b16 v[84:85], v203 offset:52224
	ds_read_b64_tr_b16 v[86:87], v203 offset:52736
	s_waitcnt lgkmcnt(14)
	v_mfma_f32_32x32x16_bf16 v[64:79], v[226:229], v[156:159], v[64:79]
	v_pk_add_f32 v[108:109], v[90:91], v[108:109]
	v_pk_add_f32 v[108:109], v[92:93], v[108:109]
	v_cvt_pk_bf16_f32 v140, v88, v89
	v_cvt_pk_bf16_f32 v141, v90, v91
	ds_read_b64_tr_b16 v[88:89], v203 offset:56320
	ds_read_b64_tr_b16 v[90:91], v203 offset:56832
	v_mfma_f32_32x32x16_bf16 v[48:63], v[230:233], v[156:159], v[48:63]
	v_pk_add_f32 v[108:109], v[94:95], v[108:109]
	v_add_f32_e32 v108, v108, v109
	v_cvt_pk_bf16_f32 v142, v92, v93
	v_cvt_pk_bf16_f32 v143, v94, v95
	s_cmp_gt_u32 s29, 6
	s_cselect_b64 s[2:3], -1, 0
	s_and_b64 s[2:3], s[48:49], s[2:3]
	s_add_i32 s54, s54, -12
	s_cmp_lt_u32 s54, -3
	s_cselect_b64 s[50:51], -1, 0
	s_and_b64 s[2:3], s[2:3], s[50:51]
	s_andn2_b64 vcc, exec, s[2:3]
	s_cbranch_vccnz .LBB0_1376
	v_add_u32_e32 v92, 64, v182
	v_cmp_lt_u32_e32 vcc, s78, v92
	v_add_u32_e32 v92, 0x60, v182
	s_nop 0
	v_cndmask_b32_e32 v64, v253, v64, vcc
	v_cmp_lt_u32_e32 vcc, s78, v92
	v_add_u32_e32 v92, 0x41, v182
	s_nop 0
	v_cndmask_b32_e32 v48, v253, v48, vcc
	v_cmp_lt_u32_e32 vcc, s78, v92
	v_add_u32_e32 v92, 0x61, v182
	s_nop 0
	v_cndmask_b32_e32 v65, v253, v65, vcc
	v_cmp_lt_u32_e32 vcc, s78, v92
	v_add_u32_e32 v92, 0x42, v182
	s_nop 0
	v_cndmask_b32_e32 v49, v253, v49, vcc
	v_cmp_lt_u32_e32 vcc, s78, v92
	v_add_u32_e32 v92, 0x62, v182
	s_nop 0
	v_cndmask_b32_e32 v66, v253, v66, vcc
	v_cmp_lt_u32_e32 vcc, s78, v92
	v_add_u32_e32 v92, 0x43, v182
	s_nop 0
	v_cndmask_b32_e32 v50, v253, v50, vcc
	v_cmp_lt_u32_e32 vcc, s78, v92
	v_add_u32_e32 v92, 0x63, v182
	s_nop 0
	v_cndmask_b32_e32 v67, v253, v67, vcc
	v_cmp_lt_u32_e32 vcc, s78, v92
	v_add_u32_e32 v92, 0x48, v182
	s_nop 0
	v_cndmask_b32_e32 v51, v253, v51, vcc
	v_cmp_lt_u32_e32 vcc, s78, v92
	v_add_u32_e32 v92, 0x68, v182
	s_nop 0
	v_cndmask_b32_e32 v68, v253, v68, vcc
	v_cmp_lt_u32_e32 vcc, s78, v92
	v_add_u32_e32 v92, 0x49, v182
	s_nop 0
	v_cndmask_b32_e32 v52, v253, v52, vcc
	v_cmp_lt_u32_e32 vcc, s78, v92
	v_add_u32_e32 v92, 0x69, v182
	s_nop 0
	v_cndmask_b32_e32 v69, v253, v69, vcc
	v_cmp_lt_u32_e32 vcc, s78, v92
	v_add_u32_e32 v92, 0x4a, v182
	s_nop 0
	v_cndmask_b32_e32 v53, v253, v53, vcc
	v_cmp_lt_u32_e32 vcc, s78, v92
	v_add_u32_e32 v92, 0x6a, v182
	s_nop 0
	v_cndmask_b32_e32 v70, v253, v70, vcc
	v_cmp_lt_u32_e32 vcc, s78, v92
	v_add_u32_e32 v92, 0x4b, v182
	s_nop 0
	v_cndmask_b32_e32 v54, v253, v54, vcc
	v_cmp_lt_u32_e32 vcc, s78, v92
	v_add_u32_e32 v92, 0x6b, v182
	s_nop 0
	v_cndmask_b32_e32 v71, v253, v71, vcc
	v_cmp_lt_u32_e32 vcc, s78, v92
	v_add_u32_e32 v92, 0x50, v182
	s_nop 0
	v_cndmask_b32_e32 v55, v253, v55, vcc
	v_cmp_lt_u32_e32 vcc, s78, v92
	v_add_u32_e32 v92, 0x70, v182
	s_nop 0
	v_cndmask_b32_e32 v72, v253, v72, vcc
	v_cmp_lt_u32_e32 vcc, s78, v92
	v_add_u32_e32 v92, 0x51, v182
	s_nop 0
	v_cndmask_b32_e32 v56, v253, v56, vcc
	v_cmp_lt_u32_e32 vcc, s78, v92
	v_add_u32_e32 v92, 0x71, v182
	s_nop 0
	v_cndmask_b32_e32 v73, v253, v73, vcc
	v_cmp_lt_u32_e32 vcc, s78, v92
	v_add_u32_e32 v92, 0x52, v182
	s_nop 0
	v_cndmask_b32_e32 v57, v253, v57, vcc
	v_cmp_lt_u32_e32 vcc, s78, v92
	v_add_u32_e32 v92, 0x72, v182
	s_nop 0
	v_cndmask_b32_e32 v74, v253, v74, vcc
	v_cmp_lt_u32_e32 vcc, s78, v92
	v_add_u32_e32 v92, 0x53, v182
	s_nop 0
	v_cndmask_b32_e32 v58, v253, v58, vcc
	v_cmp_lt_u32_e32 vcc, s78, v92
	v_add_u32_e32 v92, 0x73, v182
	s_nop 0
	v_cndmask_b32_e32 v75, v253, v75, vcc
	v_cmp_lt_u32_e32 vcc, s78, v92
	v_add_u32_e32 v92, 0x58, v182
	s_nop 0
	v_cndmask_b32_e32 v59, v253, v59, vcc
	v_cmp_lt_u32_e32 vcc, s78, v92
	v_add_u32_e32 v92, 0x78, v182
	s_nop 0
	v_cndmask_b32_e32 v76, v253, v76, vcc
	v_cmp_lt_u32_e32 vcc, s78, v92
	v_add_u32_e32 v92, 0x59, v182
	s_nop 0
	v_cndmask_b32_e32 v60, v253, v60, vcc
	v_cmp_lt_u32_e32 vcc, s78, v92
	v_add_u32_e32 v92, 0x79, v182
	s_nop 0
	v_cndmask_b32_e32 v77, v253, v77, vcc
	v_cmp_lt_u32_e32 vcc, s78, v92
	v_add_u32_e32 v92, 0x5a, v182
	s_nop 0
	v_cndmask_b32_e32 v61, v253, v61, vcc
	v_cmp_lt_u32_e32 vcc, s78, v92
	v_add_u32_e32 v92, 0x7a, v182
	s_nop 0
	v_cndmask_b32_e32 v78, v253, v78, vcc
	v_cmp_lt_u32_e32 vcc, s78, v92
	v_add_u32_e32 v92, 0x5b, v182
	s_nop 0
	v_cndmask_b32_e32 v62, v253, v62, vcc
	v_cmp_lt_u32_e32 vcc, s78, v92
	v_add_u32_e32 v92, 0x7b, v182
	s_nop 0
	v_cndmask_b32_e32 v79, v253, v79, vcc
	v_cmp_lt_u32_e32 vcc, s78, v92
	s_nop 1
	v_cndmask_b32_e32 v63, v253, v63, vcc
